# phase-0 gate_up weight transposes: item index remapped so a workgroup's 8 waves cover 2 column blocks x 4 k-blocks (512-B contiguous reads and writes); plus the phase-0 nt loads
# speedup vs baseline: 1.0053x; 1.0053x over previous
; #define LAS __attribute__((address_space(3)))
; #define SCHED_FENCE() __builtin_amdgcn_sched_barrier(0)
; __device__ __forceinline__ void transpose_item(const float* W, int K, int N, bf16_t* WT, int kb, int nbd, int src0, LAS float* scr, int lane, const float* gk = nullptr) {
;     const int k0 = kb * 64;
;     const float* wp = W + (size_t)(k0 + (lane >> 4)) * N + src0 + (lane & 15) * 4;
;     f32x4 v[16];
; #pragma unroll
;     for (int i = 0; i < 16; ++i) v[i] = *(const f32x4*)(wp + (size_t)(4 * i) * N);
;     SCHED_FENCE();
; #pragma unroll
;     for (int i = 0; i < 16; ++i) { if (gk) v[i] = v[i] * gk[k0 + 4 * i + (lane >> 4)];
;         LAS float* s = scr + (4 * i + (lane >> 4)) * 65 + (lane & 15) * 4; s[0] = v[i].x; s[1] = v[i].y; s[2] = v[i].z; s[3] = v[i].w; }
; __global__ void __launch_bounds__(512, 2) fwd_kernel(Args a) {
;     ...
;             for (int it = gw; it < NITEMS; it += ngw) {
;                 int r = it;
;                 if (r < I_GU) { const int nb = r % 176; transpose_item(P.in[3], DM, NGU, (bf16_t*)(ws + WS_WGU1), r / 176, nb, map_gu(nb), scr, lane, P.in[2]); continue; } r -= I_GU;
;                 if (r < I_GU) { const int nb = r % 176; transpose_item(P.in[21], DM, NGU, (bf16_t*)(ws + WS_WGU2), r / 176, nb, map_gu(nb), scr, lane, P.in[20]); continue; } r -= I_GU;
.LBB0_257:
	s_mov_b32 s28, s100
	s_add_i32 s28, s28, s46
	s_add_i32 s10, s10, s11
	s_add_i32 s23, s23, s12
	s_add_i32 s13, s13, s18
	s_add_i32 s19, s19, s22
	s_cmpk_gt_i32 s28, 0x50ff
	s_cbranch_scc1 .LBB0_386
.LBB0_258:
	s_mov_b32 s100, s28
	s_cmpk_gt_u32 s28, 0x2bff
	s_cbranch_scc1 .Lmap_done
	s_cmpk_gt_u32 s28, 0x15ff
	s_cselect_b32 s7, 0x1600, 0
	s_sub_u32 s8, s28, s7
	s_and_b32 s9, s8, 7
	s_lshr_b32 s8, s8, 3
	s_mul_i32 s28, s8, 0x2e9
	s_lshr_b32 s28, s28, 16
	s_mul_i32 s6, s28, 88
	s_sub_u32 s8, s8, s6
	s_lshl_b32 s8, s8, 1
	s_and_b32 s6, s9, 1
	s_add_u32 s8, s8, s6
	s_lshl_b32 s28, s28, 2
	s_lshr_b32 s9, s9, 1
	s_add_u32 s28, s28, s9
	s_mul_i32 s28, s28, 0xb0
	s_add_u32 s28, s28, s8
	s_add_u32 s28, s28, s7
.Lmap_done:
	s_lshl_b32 s10, s28, 5
	s_lshl_b32 s23, s28, 6
	s_lshl_b32 s13, s28, 1
	s_lshl_b32 s19, s28, 2
	s_cmpk_gt_i32 s28, 0x15ff
	s_mov_b64 s[6:7], -1
	s_cbranch_scc0 .LBB0_337
	s_cmpk_gt_u32 s28, 0x2bff
	s_cbranch_scc0 .LBB0_310
	s_cmpk_gt_u32 s28, 0x36ff
	s_cbranch_scc0 .LBB0_307
	s_cmpk_gt_u32 s28, 0x41ff
	s_cbranch_scc0 .LBB0_304
	s_cmpk_gt_u32 s28, 0x4aff
	s_cbranch_scc0 .LBB0_268
	s_cmpk_gt_u32 s28, 0x4cff
	s_cbranch_scc0 .LBB0_265
	s_load_dwordx2 s[30:31], s[40:41], 0x90
	s_and_b32 s6, s13, 0x7fffffc0
	s_add_i32 s6, s6, 0xffff6600
	v_or_b32_e32 v144, s6, v92
	s_and_b32 s8, s23, 0x7c0
	v_lshlrev_b64 v[0:1], 13, v[144:145]
	s_waitcnt lgkmcnt(0)
	v_lshl_add_u64 v[0:1], s[30:31], 0, v[0:1]
	s_lshl_b32 s74, s8, 2
	v_lshl_add_u64 v[0:1], v[0:1], 0, s[74:75]
	v_lshlrev_b32_e32 v144, 2, v70
	v_lshl_add_u64 v[56:57], v[0:1], 0, v[144:145]
	v_add_co_u32_e32 v4, vcc, 0x8000, v56
	s_mov_b32 s0, 0x18000
	s_nop 0
	v_addc_co_u32_e32 v5, vcc, 0, v57, vcc
	v_add_co_u32_e32 v8, vcc, s47, v56
	global_load_dwordx4 v[0:3], v[56:57], off nt
	s_nop 0
	global_load_dwordx4 v[4:7], v[4:5], off nt
	v_addc_co_u32_e32 v9, vcc, 0, v57, vcc
	v_add_co_u32_e32 v12, vcc, s0, v56
	s_mov_b32 s0, 0x48000
	s_nop 0
	v_addc_co_u32_e32 v13, vcc, 0, v57, vcc
	v_add_co_u32_e32 v16, vcc, 0x20000, v56
	global_load_dwordx4 v[8:11], v[8:9], off nt
	s_nop 0
	global_load_dwordx4 v[12:15], v[12:13], off nt
	v_addc_co_u32_e32 v17, vcc, 0, v57, vcc
	v_add_co_u32_e32 v20, vcc, 0x28000, v56
	s_nop 1
	v_addc_co_u32_e32 v21, vcc, 0, v57, vcc
	v_add_co_u32_e32 v24, vcc, s3, v56
	global_load_dwordx4 v[16:19], v[16:17], off nt
	s_nop 0
	global_load_dwordx4 v[20:23], v[20:21], off nt
	v_addc_co_u32_e32 v25, vcc, 0, v57, vcc
	v_add_co_u32_e32 v28, vcc, 0x38000, v56
	s_nop 1
	v_addc_co_u32_e32 v29, vcc, 0, v57, vcc
	v_add_co_u32_e32 v32, vcc, s21, v56
	global_load_dwordx4 v[24:27], v[24:25], off nt
	s_nop 0
	global_load_dwordx4 v[28:31], v[28:29], off nt
	v_addc_co_u32_e32 v33, vcc, 0, v57, vcc
	v_add_co_u32_e32 v36, vcc, s0, v56
	s_mov_b32 s0, 0x58000
	s_nop 0
	v_addc_co_u32_e32 v37, vcc, 0, v57, vcc
	v_add_co_u32_e32 v40, vcc, s20, v56
	global_load_dwordx4 v[32:35], v[32:33], off nt
	s_nop 0
	global_load_dwordx4 v[36:39], v[36:37], off nt
	v_addc_co_u32_e32 v41, vcc, 0, v57, vcc
	v_add_co_u32_e32 v44, vcc, s0, v56
	s_mov_b32 s0, 0x68000
	s_nop 0
	v_addc_co_u32_e32 v45, vcc, 0, v57, vcc
	v_add_co_u32_e32 v48, vcc, s26, v56
	global_load_dwordx4 v[40:43], v[40:41], off nt
	s_nop 0
	global_load_dwordx4 v[44:47], v[44:45], off nt
	v_addc_co_u32_e32 v49, vcc, 0, v57, vcc
	v_add_co_u32_e32 v52, vcc, s0, v56
	s_mov_b32 s0, 0x78000
	s_nop 0
	v_addc_co_u32_e32 v53, vcc, 0, v57, vcc
	v_add_co_u32_e32 v58, vcc, s48, v56
	global_load_dwordx4 v[48:51], v[48:49], off nt
	s_nop 0
	global_load_dwordx4 v[52:55], v[52:53], off nt
	v_addc_co_u32_e32 v59, vcc, 0, v57, vcc
	v_add_co_u32_e32 v60, vcc, s0, v56
	s_nop 1
	v_addc_co_u32_e32 v61, vcc, 0, v57, vcc
	global_load_dwordx4 v[56:59], v[58:59], off nt
	s_nop 0
	global_load_dwordx4 v[60:63], v[60:61], off nt
	s_waitcnt vmcnt(15)
	ds_write2_b32 v93, v0, v1 offset1:1
	ds_write2_b32 v93, v2, v3 offset0:2 offset1:3
	v_add_u32_e32 v0, 0x410, v93
	s_waitcnt vmcnt(14)
	ds_write2_b32 v0, v4, v5 offset1:1
	v_add_u32_e32 v0, 0x418, v93
	ds_write2_b32 v0, v6, v7 offset1:1
	v_add_u32_e32 v0, 0x820, v93
	s_waitcnt vmcnt(13)
	ds_write2_b32 v0, v8, v9 offset1:1
	v_add_u32_e32 v0, 0x828, v93
	ds_write2_b32 v0, v10, v11 offset1:1
	v_add_u32_e32 v0, 0xc30, v93
	s_waitcnt vmcnt(12)
	ds_write2_b32 v0, v12, v13 offset1:1
	v_add_u32_e32 v0, 0xc38, v93
	ds_write2_b32 v0, v14, v15 offset1:1
	v_add_u32_e32 v0, 0x1040, v93
	s_waitcnt vmcnt(11)
	ds_write2_b32 v0, v16, v17 offset1:1
	v_add_u32_e32 v0, 0x1048, v93
	ds_write2_b32 v0, v18, v19 offset1:1
	v_add_u32_e32 v0, 0x1450, v93
	s_waitcnt vmcnt(10)
	ds_write2_b32 v0, v20, v21 offset1:1
	v_add_u32_e32 v0, 0x1458, v93
	ds_write2_b32 v0, v22, v23 offset1:1
	v_add_u32_e32 v0, 0x1860, v93
	s_waitcnt vmcnt(9)
	ds_write2_b32 v0, v24, v25 offset1:1
	v_add_u32_e32 v0, 0x1868, v93
	ds_write2_b32 v0, v26, v27 offset1:1
	v_add_u32_e32 v0, 0x1c70, v93
	s_waitcnt vmcnt(8)
	ds_write2_b32 v0, v28, v29 offset1:1
	v_add_u32_e32 v0, 0x1c78, v93
	ds_write2_b32 v0, v30, v31 offset1:1
	v_add_u32_e32 v0, 0x2080, v93
	s_waitcnt vmcnt(7)
	ds_write2_b32 v0, v32, v33 offset1:1
	v_add_u32_e32 v0, 0x2088, v93
	ds_write2_b32 v0, v34, v35 offset1:1
	v_add_u32_e32 v0, 0x2490, v93
	s_waitcnt vmcnt(6)
; #define LAS __attribute__((address_space(3)))
; __device__ __forceinline__ unsigned pk2(float lo, float hi) { unsigned r; asm("v_cvt_pk_bf16_f32 %0, %1, %2" : "=v"(r) : "v"(lo), "v"(hi)); return r; }
; __device__ __forceinline__ void transpose_item(const float* W, int K, int N, bf16_t* WT, int kb, int nbd, int src0, LAS float* scr, int lane, const float* gk = nullptr) {
;     ...
;         LAS float* s = scr + (4 * i + (lane >> 4)) * 65 + (lane & 15) * 4; s[0] = v[i].x; s[1] = v[i].y; s[2] = v[i].z; s[3] = v[i].w; }
;     const int c = lane & 7;
; #pragma unroll
;     for (int jj = 0; jj < 8; ++jj) {
;         const int n = (lane >> 3) + 8 * jj; const LAS float* s = scr + (8 * c) * 65 + n;
;         u32x4 o; o.x = pk2(s[0], s[65]); o.y = pk2(s[2 * 65], s[3 * 65]); o.z = pk2(s[4 * 65], s[5 * 65]); o.w = pk2(s[6 * 65], s[7 * 65]);
;         *(u32x4*)(WT + (size_t)(nbd * 64 + n) * K + k0 + 8 * c) = o;
;     }
	ds_write2_b32 v0, v36, v37 offset1:1
	v_add_u32_e32 v0, 0x2498, v93
	ds_write2_b32 v0, v38, v39 offset1:1
	v_add_u32_e32 v0, 0x28a0, v93
	s_waitcnt vmcnt(5)
	ds_write2_b32 v0, v40, v41 offset1:1
	v_add_u32_e32 v0, 0x28a8, v93
	ds_write2_b32 v0, v42, v43 offset1:1
	v_add_u32_e32 v0, 0x2cb0, v93
	s_waitcnt vmcnt(4)
	ds_write2_b32 v0, v44, v45 offset1:1
	v_add_u32_e32 v0, 0x2cb8, v93
	ds_write2_b32 v0, v46, v47 offset1:1
	v_add_u32_e32 v0, 0x30c0, v93
	s_waitcnt vmcnt(3)
	ds_write2_b32 v0, v48, v49 offset1:1
	v_add_u32_e32 v0, 0x30c8, v93
	ds_write2_b32 v0, v50, v51 offset1:1
	v_add_u32_e32 v0, 0x34d0, v93
	s_waitcnt vmcnt(2)
	ds_write2_b32 v0, v52, v53 offset1:1
	v_add_u32_e32 v0, 0x34d8, v93
	ds_write2_b32 v0, v54, v55 offset1:1
	v_add_u32_e32 v0, 0x38e0, v93
	s_waitcnt vmcnt(1)
	ds_write2_b32 v0, v56, v57 offset1:1
	v_add_u32_e32 v0, 0x38e8, v93
	ds_write2_b32 v0, v58, v59 offset1:1
	v_add_u32_e32 v0, 0x3cf0, v93
	s_waitcnt vmcnt(0)
	ds_write2_b32 v0, v60, v61 offset1:1
	v_add_u32_e32 v0, 0x3cf8, v93
	ds_write2_b32 v0, v62, v63 offset1:1
	ds_read2_b32 v[4:5], v95 offset0:65 offset1:73
	ds_read2_b32 v[6:7], v95 offset1:8
	ds_read2_b32 v[8:9], v95 offset0:130 offset1:138
	ds_read2_b32 v[10:11], v95 offset0:195 offset1:203
	v_add_u32_e32 v24, 0x400, v95
	ds_read2_b32 v[12:13], v24 offset0:4 offset1:12
	ds_read2_b32 v[14:15], v24 offset0:69 offset1:77
	ds_read2_b32 v[16:17], v24 offset0:134 offset1:142
	ds_read2_b32 v[18:19], v24 offset0:199 offset1:207
	s_mov_b32 s7, s75
	s_waitcnt lgkmcnt(6)
	v_cvt_pk_bf16_f32 v0, v6, v4
	v_or_b32_e32 v4, s8, v94
	v_lshl_add_u64 v[20:21], s[6:7], 1, v[72:73]
	v_lshlrev_b32_e32 v144, 12, v4
	v_lshl_add_u64 v[22:23], v[20:21], 0, v[144:145]
	s_waitcnt lgkmcnt(4)
	v_cvt_pk_bf16_f32 v1, v8, v10
	s_waitcnt lgkmcnt(2)
	v_cvt_pk_bf16_f32 v2, v12, v14
	s_waitcnt lgkmcnt(0)
	v_cvt_pk_bf16_f32 v3, v16, v18
	global_store_dwordx4 v[22:23], v[0:3], off
	v_or_b32_e32 v4, s8, v96
	v_lshlrev_b32_e32 v144, 12, v4
	v_cvt_pk_bf16_f32 v0, v7, v5
	v_cvt_pk_bf16_f32 v1, v9, v11
	v_cvt_pk_bf16_f32 v2, v13, v15
	v_cvt_pk_bf16_f32 v3, v17, v19
	ds_read2_b32 v[6:7], v95 offset0:16 offset1:24
	ds_read2_b32 v[8:9], v95 offset0:81 offset1:89
	ds_read2_b32 v[10:11], v95 offset0:146 offset1:154
	ds_read2_b32 v[12:13], v95 offset0:211 offset1:219
	ds_read2_b32 v[14:15], v24 offset0:20 offset1:28
	ds_read2_b32 v[16:17], v24 offset0:85 offset1:93
	ds_read2_b32 v[18:19], v24 offset0:150 offset1:158
	ds_read2_b32 v[22:23], v24 offset0:215 offset1:223
	v_lshl_add_u64 v[4:5], v[20:21], 0, v[144:145]
	global_store_dwordx4 v[4:5], v[0:3], off
	v_or_b32_e32 v4, s8, v97
	v_lshlrev_b32_e32 v144, 12, v4
	v_lshl_add_u64 v[4:5], v[20:21], 0, v[144:145]
	s_waitcnt lgkmcnt(6)
	v_cvt_pk_bf16_f32 v0, v6, v8
	s_waitcnt lgkmcnt(4)
	v_cvt_pk_bf16_f32 v1, v10, v12
	s_waitcnt lgkmcnt(2)
	v_cvt_pk_bf16_f32 v2, v14, v16
	s_waitcnt lgkmcnt(0)
	v_cvt_pk_bf16_f32 v3, v18, v22
	global_store_dwordx4 v[4:5], v[0:3], off
	v_or_b32_e32 v4, s8, v98
	v_lshlrev_b32_e32 v144, 12, v4
	v_cvt_pk_bf16_f32 v0, v7, v9
	v_cvt_pk_bf16_f32 v1, v11, v13
	v_cvt_pk_bf16_f32 v2, v15, v17
	v_cvt_pk_bf16_f32 v3, v19, v23
	ds_read2_b32 v[6:7], v95 offset0:32 offset1:40
	ds_read2_b32 v[8:9], v95 offset0:97 offset1:105
	ds_read2_b32 v[10:11], v95 offset0:162 offset1:170
	ds_read2_b32 v[12:13], v95 offset0:227 offset1:235
	ds_read2_b32 v[14:15], v24 offset0:36 offset1:44
	ds_read2_b32 v[16:17], v24 offset0:101 offset1:109
	ds_read2_b32 v[18:19], v24 offset0:166 offset1:174
	ds_read2_b32 v[22:23], v24 offset0:231 offset1:239
	v_lshl_add_u64 v[4:5], v[20:21], 0, v[144:145]
	global_store_dwordx4 v[4:5], v[0:3], off
	v_or_b32_e32 v4, s8, v99
	v_lshlrev_b32_e32 v144, 12, v4
	v_lshl_add_u64 v[4:5], v[20:21], 0, v[144:145]
	s_waitcnt lgkmcnt(6)
	v_cvt_pk_bf16_f32 v0, v6, v8
	s_waitcnt lgkmcnt(4)
	v_cvt_pk_bf16_f32 v1, v10, v12
	s_waitcnt lgkmcnt(2)
	v_cvt_pk_bf16_f32 v2, v14, v16
	s_waitcnt lgkmcnt(0)
	v_cvt_pk_bf16_f32 v3, v18, v22
	global_store_dwordx4 v[4:5], v[0:3], off
	v_or_b32_e32 v4, s8, v100
	v_lshlrev_b32_e32 v144, 12, v4
	v_cvt_pk_bf16_f32 v0, v7, v9
	v_cvt_pk_bf16_f32 v1, v11, v13
	v_cvt_pk_bf16_f32 v2, v15, v17
	v_cvt_pk_bf16_f32 v3, v19, v23
	ds_read2_b32 v[6:7], v95 offset0:48 offset1:56
	ds_read2_b32 v[8:9], v95 offset0:113 offset1:121
	ds_read2_b32 v[10:11], v95 offset0:178 offset1:186
	ds_read2_b32 v[12:13], v95 offset0:243 offset1:251
	ds_read2_b32 v[14:15], v24 offset0:52 offset1:60
	ds_read2_b32 v[16:17], v24 offset0:117 offset1:125
	ds_read2_b32 v[18:19], v24 offset0:182 offset1:190
	ds_read2_b32 v[22:23], v24 offset0:247 offset1:255
	v_lshl_add_u64 v[4:5], v[20:21], 0, v[144:145]
	global_store_dwordx4 v[4:5], v[0:3], off
	v_or_b32_e32 v4, s8, v101
	v_lshlrev_b32_e32 v144, 12, v4
	v_lshl_add_u64 v[4:5], v[20:21], 0, v[144:145]
	s_waitcnt lgkmcnt(6)
	v_cvt_pk_bf16_f32 v0, v6, v8
	s_waitcnt lgkmcnt(4)
	v_cvt_pk_bf16_f32 v1, v10, v12
	s_waitcnt lgkmcnt(2)
	v_cvt_pk_bf16_f32 v2, v14, v16
	s_waitcnt lgkmcnt(0)
	v_cvt_pk_bf16_f32 v3, v18, v22
	global_store_dwordx4 v[4:5], v[0:3], off
	v_or_b32_e32 v4, s8, v102
	v_lshlrev_b32_e32 v144, 12, v4
	v_lshl_add_u64 v[4:5], v[20:21], 0, v[144:145]
	v_cvt_pk_bf16_f32 v0, v7, v9
	v_cvt_pk_bf16_f32 v1, v11, v13
	v_cvt_pk_bf16_f32 v2, v15, v17
	v_cvt_pk_bf16_f32 v3, v19, v23
	global_store_dwordx4 v[4:5], v[0:3], off
	s_mov_b64 s[6:7], 0

; __global__ void __launch_bounds__(512, 2) fwd_kernel(Args a) {
	.amdhsa_kernel _Z10fwd_kernel4Args
		.amdhsa_group_segment_fixed_size 0
		.amdhsa_private_segment_fixed_size 0
		.amdhsa_kernarg_size 480
		.amdhsa_user_sgpr_count 2
		.amdhsa_user_sgpr_dispatch_ptr 0
		.amdhsa_user_sgpr_queue_ptr 0
		.amdhsa_user_sgpr_kernarg_segment_ptr 1
		.amdhsa_user_sgpr_dispatch_id 0
		.amdhsa_user_sgpr_kernarg_preload_length 0
		.amdhsa_user_sgpr_kernarg_preload_offset 0
		.amdhsa_user_sgpr_private_segment_size 0
		.amdhsa_uses_dynamic_stack 0
		.amdhsa_enable_private_segment 0
		.amdhsa_system_sgpr_workgroup_id_x 1
		.amdhsa_system_sgpr_workgroup_id_y 0
		.amdhsa_system_sgpr_workgroup_id_z 0
		.amdhsa_system_sgpr_workgroup_info 0
		.amdhsa_system_vgpr_workitem_id 2
		.amdhsa_next_free_vgpr 254
		.amdhsa_next_free_sgpr 102
		.amdhsa_accum_offset 256
		.amdhsa_reserve_vcc 1
		.amdhsa_float_round_mode_32 0
		.amdhsa_float_round_mode_16_64 0
		.amdhsa_float_denorm_mode_32 3
		.amdhsa_float_denorm_mode_16_64 3
		.amdhsa_dx10_clamp 1
		.amdhsa_ieee_mode 1
		.amdhsa_fp16_overflow 0
		.amdhsa_tg_split 0
		.amdhsa_exception_fp_ieee_invalid_op 0
		.amdhsa_exception_fp_denorm_src 0
		.amdhsa_exception_fp_ieee_div_zero 0
		.amdhsa_exception_fp_ieee_overflow 0
		.amdhsa_exception_fp_ieee_underflow 0
		.amdhsa_exception_fp_ieee_inexact 0
		.amdhsa_exception_int_div_zero 0
	.end_amdhsa_kernel

; __global__ void __launch_bounds__(512, 2) fwd_kernel(Args a) {
amdhsa.kernels:
  - .agpr_count:     0
    .args:
      - .offset:         0
        .size:           224
        .value_kind:     by_value
      - .offset:         224
        .size:           4
        .value_kind:     hidden_block_count_x
      - .offset:         228
        .size:           4
        .value_kind:     hidden_block_count_y
      - .offset:         232
        .size:           4
        .value_kind:     hidden_block_count_z
      - .offset:         236
        .size:           2
        .value_kind:     hidden_group_size_x
      - .offset:         238
        .size:           2
        .value_kind:     hidden_group_size_y
      - .offset:         240
        .size:           2
        .value_kind:     hidden_group_size_z
      - .offset:         242
        .size:           2
        .value_kind:     hidden_remainder_x
      - .offset:         244
        .size:           2
        .value_kind:     hidden_remainder_y
      - .offset:         246
        .size:           2
        .value_kind:     hidden_remainder_z
      - .offset:         264
        .size:           8
        .value_kind:     hidden_global_offset_x
      - .offset:         272
        .size:           8
        .value_kind:     hidden_global_offset_y
      - .offset:         280
        .size:           8
        .value_kind:     hidden_global_offset_z
      - .offset:         288
        .size:           2
        .value_kind:     hidden_grid_dims
      - .offset:         312
        .size:           8
        .value_kind:     hidden_multigrid_sync_arg
      - .offset:         344
        .size:           4
        .value_kind:     hidden_dynamic_lds_size
    .group_segment_fixed_size: 0
    .kernarg_segment_align: 8
    .kernarg_segment_size: 480
    .language:       OpenCL C
    .language_version:
      - 2
      - 0
    .max_flat_workgroup_size: 512
    .name:           _Z10fwd_kernel4Args
    .private_segment_fixed_size: 0
    .sgpr_count:     108
    .sgpr_spill_count: 211
    .symbol:         _Z10fwd_kernel4Args.kd
    .uniform_work_group_size: 1
    .uses_dynamic_stack: false
    .vgpr_count:     254
    .vgpr_spill_count: 0
    .wavefront_size: 64
